# P1 modulation pass: the f32 activation rows are read with the nt (streaming) hint so the bf16 h image it writes stays cached for the in-projection
# speedup vs baseline: 1.0750x; 1.0083x over previous
.LBB0_153:
	s_mul_i32 s8, s4, 0xc00
	s_ashr_i32 s9, s8, 31
	s_lshl_b64 s[8:9], s[8:9], 2
	v_readlane_b32 s34, v250, 0
	v_readlane_b32 s35, v250, 1
	s_add_u32 s8, s34, s8
	s_addc_u32 s9, s35, s9
	v_lshl_add_u64 v[0:1], s[8:9], 0, v[6:7]
	v_add_co_u32_e32 v0, vcc, 0x1000, v0
	v_lshl_add_u64 v[48:49], s[6:7], 0, v[6:7]
	s_nop 0
	v_addc_co_u32_e32 v1, vcc, 0, v1, vcc
	v_add_co_u32_e32 v20, vcc, 0x1000, v48
	global_load_dwordx4 v[12:15], v[0:1], off offset:256 nt
	s_nop 0
	v_addc_co_u32_e32 v21, vcc, 0, v49, vcc
	v_add_co_u32_e32 v24, vcc, 0x2000, v48
	global_load_dwordx4 v[0:3], v6, s[8:9] offset:256
	global_load_dwordx4 v[16:19], v6, s[6:7]
	v_addc_co_u32_e32 v25, vcc, 0, v49, vcc
	v_add_co_u32_e32 v28, vcc, 0x3000, v48
	global_load_dwordx4 v[20:23], v[20:21], off nt
	s_nop 0
	v_addc_co_u32_e32 v29, vcc, 0, v49, vcc
	v_add_co_u32_e32 v32, vcc, 0x4000, v48
	global_load_dwordx4 v[24:27], v[24:25], off nt
	s_nop 0
	v_addc_co_u32_e32 v33, vcc, 0, v49, vcc
	global_load_dwordx4 v[28:31], v[28:29], off nt
	v_add_co_u32_e32 v36, vcc, 0x5000, v48
	global_load_dwordx4 v[32:35], v[32:33], off nt
	s_nop 0
	v_addc_co_u32_e32 v37, vcc, 0, v49, vcc
	global_load_dwordx4 v[36:39], v[36:37], off nt
	v_add_co_u32_e32 v40, vcc, 0x6000, v48
	s_lshl_b64 s[6:7], s[0:1], 11
	s_nop 0
	v_addc_co_u32_e32 v41, vcc, 0, v49, vcc
	global_load_dwordx4 v[40:43], v[40:41], off nt
	v_add_co_u32_e32 v44, vcc, 0x7000, v48
	v_lshl_add_u64 v[50:51], v[4:5], 0, s[6:7]
	s_nop 0
	v_addc_co_u32_e32 v45, vcc, 0, v49, vcc
	global_load_dwordx4 v[44:47], v[44:45], off nt
	v_add_co_u32_e32 v52, vcc, s10, v50
	s_add_i32 s23, s23, s84
	s_nop 0
	v_addc_co_u32_e32 v53, vcc, 0, v51, vcc
	v_add_co_u32_e32 v54, vcc, s11, v50
	s_add_i32 s0, s0, s3
	s_nop 0
	v_addc_co_u32_e32 v55, vcc, 0, v51, vcc
	s_cmpk_gt_i32 s23, 0x807
	s_waitcnt vmcnt(9)
	v_pk_add_f32 v[56:57], v[12:13], 1.0 op_sel_hi:[1,0]
	v_pk_add_f32 v[58:59], v[14:15], 1.0 op_sel_hi:[1,0]
	s_waitcnt vmcnt(7)
	v_pk_fma_f32 v[12:13], v[56:57], v[16:17], v[0:1]
	v_pk_fma_f32 v[14:15], v[58:59], v[18:19], v[2:3]
	v_cvt_pk_bf16_f32 v12, v12, v13
	v_cvt_pk_bf16_f32 v13, v14, v15
	s_waitcnt vmcnt(6)
	v_pk_fma_f32 v[16:17], v[56:57], v[20:21], v[0:1]
	v_pk_fma_f32 v[18:19], v[58:59], v[22:23], v[2:3]
	v_cvt_pk_bf16_f32 v14, v16, v17
	v_cvt_pk_bf16_f32 v15, v18, v19
	global_store_dwordx2 v[50:51], v[12:13], off
	global_store_dwordx2 v[50:51], v[14:15], off offset:2048
	s_waitcnt vmcnt(7)
	v_pk_fma_f32 v[16:17], v[56:57], v[24:25], v[0:1]
	v_pk_fma_f32 v[18:19], v[58:59], v[26:27], v[2:3]
	v_cvt_pk_bf16_f32 v12, v16, v17
	v_cvt_pk_bf16_f32 v13, v18, v19
	s_waitcnt vmcnt(6)
	v_pk_fma_f32 v[14:15], v[56:57], v[28:29], v[0:1]
	v_pk_fma_f32 v[16:17], v[58:59], v[30:31], v[2:3]
	global_store_dwordx2 v[54:55], v[12:13], off offset:-4096
	v_cvt_pk_bf16_f32 v12, v14, v15
	v_cvt_pk_bf16_f32 v13, v16, v17
	s_waitcnt vmcnt(6)
	v_pk_fma_f32 v[14:15], v[56:57], v[32:33], v[0:1]
	v_pk_fma_f32 v[16:17], v[58:59], v[34:35], v[2:3]
	global_store_dwordx2 v[52:53], v[12:13], off offset:2048
	v_cvt_pk_bf16_f32 v12, v14, v15
	v_cvt_pk_bf16_f32 v13, v16, v17
	s_waitcnt vmcnt(6)
	v_pk_fma_f32 v[14:15], v[56:57], v[36:37], v[0:1]
	global_store_dwordx2 v[54:55], v[12:13], off
	v_cvt_pk_bf16_f32 v12, v14, v15
	v_pk_fma_f32 v[14:15], v[58:59], v[38:39], v[2:3]
	s_waitcnt vmcnt(5)
	v_pk_fma_f32 v[16:17], v[58:59], v[46:47], v[2:3]
	v_cvt_pk_bf16_f32 v13, v14, v15
	global_store_dwordx2 v[54:55], v[12:13], off offset:2048
	v_pk_fma_f32 v[12:13], v[56:57], v[40:41], v[0:1]
	v_pk_fma_f32 v[14:15], v[58:59], v[42:43], v[2:3]
	v_cvt_pk_bf16_f32 v12, v12, v13
	v_cvt_pk_bf16_f32 v13, v14, v15
	v_add_co_u32_e32 v14, vcc, s12, v50
	s_nop 1
	v_addc_co_u32_e32 v15, vcc, 0, v51, vcc
	v_add_co_u32_e32 v52, vcc, s13, v50
	s_nop 1
	v_addc_co_u32_e32 v53, vcc, 0, v51, vcc
	v_add_co_u32_e32 v20, vcc, s19, v48
	global_store_dwordx2 v[52:53], v[12:13], off offset:-4096
	s_nop 0
	v_addc_co_u32_e32 v21, vcc, 0, v49, vcc
	v_add_co_u32_e32 v28, vcc, s20, v48
	v_pk_fma_f32 v[12:13], v[56:57], v[44:45], v[0:1]
	s_nop 0
	v_addc_co_u32_e32 v29, vcc, 0, v49, vcc
	v_cvt_pk_bf16_f32 v12, v12, v13
	v_cvt_pk_bf16_f32 v13, v16, v17
	v_add_co_u32_e32 v36, vcc, s21, v48
	global_store_dwordx2 v[14:15], v[12:13], off offset:2048
	s_nop 0
	v_addc_co_u32_e32 v37, vcc, 0, v49, vcc
	global_load_dwordx4 v[12:15], v[20:21], off offset:-4096 nt
	global_load_dwordx4 v[16:19], v[20:21], off nt
	s_nop 0
	global_load_dwordx4 v[20:23], v[28:29], off offset:-4096 nt
	global_load_dwordx4 v[24:27], v[28:29], off nt
	s_nop 0
	global_load_dwordx4 v[28:31], v[36:37], off offset:-4096 nt
	global_load_dwordx4 v[32:35], v[36:37], off nt
	v_add_co_u32_e32 v44, vcc, s22, v48
	s_waitcnt vmcnt(5)
	v_pk_fma_f32 v[12:13], v[56:57], v[12:13], v[0:1]
	v_addc_co_u32_e32 v45, vcc, 0, v49, vcc
	global_load_dwordx4 v[36:39], v[44:45], off offset:-4096 nt
	global_load_dwordx4 v[40:43], v[44:45], off nt
	v_add_co_u32_e32 v44, vcc, s16, v50
	v_pk_fma_f32 v[14:15], v[58:59], v[14:15], v[2:3]
	s_nop 0
	v_addc_co_u32_e32 v45, vcc, 0, v51, vcc
	v_add_co_u32_e32 v46, vcc, s17, v50
	s_waitcnt vmcnt(6)
	v_pk_fma_f32 v[16:17], v[56:57], v[16:17], v[0:1]
	v_pk_fma_f32 v[18:19], v[58:59], v[18:19], v[2:3]
	s_waitcnt vmcnt(5)
	v_pk_fma_f32 v[20:21], v[56:57], v[20:21], v[0:1]
	v_pk_fma_f32 v[22:23], v[58:59], v[22:23], v[2:3]
	s_waitcnt vmcnt(4)
	v_pk_fma_f32 v[24:25], v[56:57], v[24:25], v[0:1]
	v_pk_fma_f32 v[26:27], v[58:59], v[26:27], v[2:3]
	s_waitcnt vmcnt(3)
	v_pk_fma_f32 v[28:29], v[56:57], v[28:29], v[0:1]
	v_pk_fma_f32 v[30:31], v[58:59], v[30:31], v[2:3]
	s_waitcnt vmcnt(2)
	v_pk_fma_f32 v[32:33], v[56:57], v[32:33], v[0:1]
	v_pk_fma_f32 v[34:35], v[58:59], v[34:35], v[2:3]
	v_cvt_pk_bf16_f32 v12, v12, v13
	v_cvt_pk_bf16_f32 v13, v14, v15
	v_addc_co_u32_e32 v47, vcc, 0, v51, vcc
	v_cvt_pk_bf16_f32 v14, v16, v17
	v_cvt_pk_bf16_f32 v15, v18, v19
	v_cvt_pk_bf16_f32 v16, v20, v21
	v_cvt_pk_bf16_f32 v17, v22, v23
	v_cvt_pk_bf16_f32 v18, v24, v25
	v_cvt_pk_bf16_f32 v19, v26, v27
	v_cvt_pk_bf16_f32 v20, v28, v29
	v_cvt_pk_bf16_f32 v21, v30, v31
	v_cvt_pk_bf16_f32 v22, v32, v33
	v_cvt_pk_bf16_f32 v23, v34, v35
	global_store_dwordx2 v[52:53], v[12:13], off
	global_store_dwordx2 v[52:53], v[14:15], off offset:2048
	global_store_dwordx2 v[46:47], v[16:17], off offset:-4096
	global_store_dwordx2 v[44:45], v[18:19], off offset:2048
	global_store_dwordx2 v[46:47], v[20:21], off
	global_store_dwordx2 v[46:47], v[22:23], off offset:2048
	s_waitcnt vmcnt(7)
	v_pk_fma_f32 v[12:13], v[58:59], v[38:39], v[2:3]
	v_pk_fma_f32 v[36:37], v[56:57], v[36:37], v[0:1]
	v_cvt_pk_bf16_f32 v25, v12, v13
	v_add_co_u32_e32 v12, vcc, s18, v50
	s_waitcnt vmcnt(6)
	v_pk_fma_f32 v[0:1], v[56:57], v[40:41], v[0:1]
	v_pk_fma_f32 v[2:3], v[58:59], v[42:43], v[2:3]
	v_cvt_pk_bf16_f32 v24, v36, v37
	v_addc_co_u32_e32 v13, vcc, 0, v51, vcc
	v_cvt_pk_bf16_f32 v0, v0, v1
	v_cvt_pk_bf16_f32 v1, v2, v3
	global_store_dwordx2 v[12:13], v[24:25], off
	global_store_dwordx2 v[12:13], v[0:1], off offset:2048
	s_cbranch_scc1 .LBB0_158
